# s5_pass1_mfma: all 36 loads of a k-block in flight with counted vmcnt instead of one load at a time; S5 W table re-laid out in MFMA-fragment order so its loads are coalesced; plus v_rcp sigmoid in GLU
# speedup vs baseline: 1.0229x; 1.0229x over previous
.LBB0_27:
	s_or_b64 exec, exec, s[0:1]
	s_waitcnt vmcnt(0)
	v_pk_mul_f32 v[50:51], v[58:59], v[30:31] op_sel:[1,0]
	v_pk_mul_f32 v[68:69], v[58:59], v[30:31] op_sel_hi:[0,1]
	v_pk_fma_f32 v[30:31], v[58:59], v[26:27], v[50:51] op_sel_hi:[0,1,1] neg_lo:[0,0,1] neg_hi:[0,0,1]
	v_pk_fma_f32 v[50:51], v[58:59], v[26:27], v[68:69] op_sel:[1,0,0]
	v_pk_mul_f32 v[26:27], v[58:59], v[32:33] op_sel:[1,0]
	v_pk_mul_f32 v[32:33], v[58:59], v[32:33] op_sel_hi:[0,1]
	v_pk_fma_f32 v[26:27], v[58:59], v[28:29], v[26:27] op_sel_hi:[0,1,1] neg_lo:[0,0,1] neg_hi:[0,0,1]
	v_pk_fma_f32 v[28:29], v[58:59], v[28:29], v[32:33] op_sel:[1,0,0]
	v_pk_mul_f32 v[32:33], v[58:59], v[22:23] op_sel:[1,0]
	v_pk_mul_f32 v[68:69], v[58:59], v[22:23] op_sel_hi:[0,1]
	v_pk_fma_f32 v[22:23], v[58:59], v[18:19], v[32:33] op_sel_hi:[0,1,1] neg_lo:[0,0,1] neg_hi:[0,0,1]
	v_pk_fma_f32 v[32:33], v[58:59], v[18:19], v[68:69] op_sel:[1,0,0]
	v_pk_mul_f32 v[18:19], v[58:59], v[24:25] op_sel:[1,0]
	v_pk_mul_f32 v[24:25], v[58:59], v[24:25] op_sel_hi:[0,1]
	v_pk_fma_f32 v[18:19], v[58:59], v[20:21], v[18:19] op_sel_hi:[0,1,1] neg_lo:[0,0,1] neg_hi:[0,0,1]
	v_pk_fma_f32 v[20:21], v[58:59], v[20:21], v[24:25] op_sel:[1,0,0]
	v_pk_mul_f32 v[24:25], v[58:59], v[14:15] op_sel:[1,0]
	v_pk_mul_f32 v[68:69], v[58:59], v[14:15] op_sel_hi:[0,1]
	v_pk_fma_f32 v[14:15], v[58:59], v[10:11], v[24:25] op_sel_hi:[0,1,1] neg_lo:[0,0,1] neg_hi:[0,0,1]
	v_pk_fma_f32 v[24:25], v[58:59], v[10:11], v[68:69] op_sel:[1,0,0]
	v_pk_mul_f32 v[10:11], v[58:59], v[16:17] op_sel:[1,0]
	v_pk_mul_f32 v[16:17], v[58:59], v[16:17] op_sel_hi:[0,1]
	v_pk_fma_f32 v[10:11], v[58:59], v[12:13], v[10:11] op_sel_hi:[0,1,1] neg_lo:[0,0,1] neg_hi:[0,0,1]
	v_pk_fma_f32 v[12:13], v[58:59], v[12:13], v[16:17] op_sel:[1,0,0]
	v_pk_mul_f32 v[16:17], v[58:59], v[6:7] op_sel:[1,0]
	v_pk_mul_f32 v[68:69], v[58:59], v[6:7] op_sel_hi:[0,1]
	v_pk_fma_f32 v[6:7], v[58:59], v[2:3], v[16:17] op_sel_hi:[0,1,1] neg_lo:[0,0,1] neg_hi:[0,0,1]
	v_pk_fma_f32 v[16:17], v[58:59], v[2:3], v[68:69] op_sel:[1,0,0]
	v_pk_mul_f32 v[2:3], v[58:59], v[8:9] op_sel:[1,0]
	v_pk_mul_f32 v[8:9], v[58:59], v[8:9] op_sel_hi:[0,1]
	v_pk_fma_f32 v[2:3], v[58:59], v[4:5], v[2:3] op_sel_hi:[0,1,1] neg_lo:[0,0,1] neg_hi:[0,0,1]
	v_pk_fma_f32 v[4:5], v[58:59], v[4:5], v[8:9] op_sel:[1,0,0]
	v_mul_f32_e32 v8, v38, v38
	v_fmamk_f32 v9, v8, 0xb94c1982, v60
	v_fmaak_f32 v9, v8, v9, 0xbe2aaa9d
	v_mul_f32_e32 v9, v8, v9
	v_fmac_f32_e32 v38, v38, v9
	v_fmamk_f32 v9, v8, 0x37d75334, v61
	v_fmaak_f32 v9, v8, v9, 0x3d2aabf7
	v_fmaak_f32 v9, v8, v9, 0xbf000004
	v_fma_f32 v8, v8, v9, 1.0
	v_lshlrev_b32_e32 v9, 30, v53
	v_and_b32_e32 v53, 1, v53
	v_cmp_eq_u32_e64 s[0:1], 0, v53
	v_and_b32_e32 v57, 0x80000000, v9
	v_xor_b32_e32 v47, v47, v43
	v_cndmask_b32_e64 v53, v8, v38, s[0:1]
	v_xor_b32_e32 v38, 0x80000000, v38
	v_cndmask_b32_e64 v8, v38, v8, s[0:1]
	s_brev_b32 s0, 1
	v_bitop3_b32 v8, v8, v9, s0 bitop3:0x78
	v_mul_f32_e32 v9, v56, v45
	v_mul_f32_e32 v38, 0x3fb8aa3b, v9
	v_xor_b32_e32 v47, v47, v53
	v_fma_f32 v45, v9, s36, -v38
	v_rndne_f32_e32 v53, v38
	v_fmac_f32_e32 v45, 0x32a5705f, v9
	v_sub_f32_e32 v38, v38, v53
	v_add_f32_e32 v38, v38, v45
	v_exp_f32_e32 v38, v38
	v_cvt_i32_f32_e32 v45, v53
	v_xor_b32_e32 v47, v47, v57
	v_cmp_class_f32_e64 s[0:1], v43, s48
	v_add_u32_e32 v66, s22, v66
	v_ldexp_f32 v38, v38, v45
	v_cndmask_b32_e64 v8, v64, v8, s[0:1]
	v_cndmask_b32_e64 v43, v64, v47, s[0:1]
	v_cmp_ngt_f32_e64 s[0:1], s49, v9
	v_add_u32_e32 v37, s23, v37
	s_nop 0
	v_cndmask_b32_e64 v38, 0, v38, s[0:1]
	v_cmp_nlt_f32_e64 s[0:1], s50, v9
	s_nop 1
	v_cndmask_b32_e64 v9, v65, v38, s[0:1]
	v_mul_f32_e32 v58, v9, v43
	v_mul_f32_e32 v56, v9, v8
	v_lshlrev_b64 v[8:9], 18, v[54:55]
	v_lshlrev_b32_e32 v38, 12, v52
	v_and_b32_e32 v52, 7, v52
	v_pk_mul_f32 v[54:55], v[30:31], v[58:59] op_sel_hi:[1,0]
	v_lshl_add_u64 v[8:9], s[26:27], 0, v[8:9]
	v_and_b32_e32 v38, 0x38000, v38
	v_lshl_or_b32 v38, v52, 5, v38
	v_or_b32_e32 v43, 7, v41
	v_pk_mul_f32 v[52:53], v[50:51], v[58:59] op_sel_hi:[1,0]
	v_pk_fma_f32 v[68:69], v[50:51], v[56:57], v[54:55] op_sel_hi:[1,0,1]
	v_pk_mul_f32 v[54:55], v[28:29], v[58:59] op_sel_hi:[1,0]
	v_pk_mul_f32 v[76:77], v[20:21], v[58:59] op_sel_hi:[1,0]
	v_lshl_add_u64 v[8:9], v[8:9], 0, v[38:39]
	v_pk_fma_f32 v[52:53], v[30:31], v[56:57], v[52:53] op_sel_hi:[1,0,1] neg_lo:[0,0,1] neg_hi:[0,0,1]
	v_pk_fma_f32 v[54:55], v[26:27], v[56:57], v[54:55] op_sel_hi:[1,0,1] neg_lo:[0,0,1] neg_hi:[0,0,1]
	v_pk_mul_f32 v[72:73], v[32:33], v[58:59] op_sel_hi:[1,0]
	v_pk_fma_f32 v[76:77], v[18:19], v[56:57], v[76:77] op_sel_hi:[1,0,1] neg_lo:[0,0,1] neg_hi:[0,0,1]
	v_cndmask_b32_e32 v38, v41, v43, vcc
	v_pk_fma_f32 v[72:73], v[22:23], v[56:57], v[72:73] op_sel_hi:[1,0,1] neg_lo:[0,0,1] neg_hi:[0,0,1]
	v_pk_mul_f32 v[80:81], v[24:25], v[58:59] op_sel_hi:[1,0]
	v_pk_mul_f32 v[84:85], v[12:13], v[58:59] op_sel_hi:[1,0]
	v_pk_mul_f32 v[88:89], v[16:17], v[58:59] op_sel_hi:[1,0]
	v_cvt_pk_bf16_f32 v52, v52, v53
	v_cvt_pk_bf16_f32 v53, v54, v55
	v_cvt_pk_bf16_f32 v55, v76, v77
	v_lshlrev_b32_e32 v38, 9, v38
	v_pk_mul_f32 v[76:77], v[4:5], v[58:59] op_sel_hi:[1,0]
	v_pk_fma_f32 v[80:81], v[14:15], v[56:57], v[80:81] op_sel_hi:[1,0,1] neg_lo:[0,0,1] neg_hi:[0,0,1]
	v_pk_fma_f32 v[84:85], v[10:11], v[56:57], v[84:85] op_sel_hi:[1,0,1] neg_lo:[0,0,1] neg_hi:[0,0,1]
	v_pk_fma_f32 v[88:89], v[6:7], v[56:57], v[88:89] op_sel_hi:[1,0,1] neg_lo:[0,0,1] neg_hi:[0,0,1]
	v_cvt_pk_bf16_f32 v54, v72, v73
	v_lshl_add_u64 v[72:73], v[8:9], 0, v[38:39]
	v_pk_fma_f32 v[76:77], v[2:3], v[56:57], v[76:77] op_sel_hi:[1,0,1] neg_lo:[0,0,1] neg_hi:[0,0,1]
	v_pk_mul_f32 v[70:71], v[26:27], v[58:59] op_sel_hi:[1,0]
	v_pk_mul_f32 v[74:75], v[22:23], v[58:59] op_sel_hi:[1,0]
	v_pk_mul_f32 v[78:79], v[18:19], v[58:59] op_sel_hi:[1,0]
	global_store_dwordx4 v[72:73], v[52:55], off
	v_pk_fma_f32 v[70:71], v[28:29], v[56:57], v[70:71] op_sel_hi:[1,0,1]
	v_pk_fma_f32 v[74:75], v[32:33], v[56:57], v[74:75] op_sel_hi:[1,0,1]
	v_cvt_pk_bf16_f32 v52, v80, v81
	v_cvt_pk_bf16_f32 v53, v84, v85
	v_cvt_pk_bf16_f32 v54, v88, v89
	v_cvt_pk_bf16_f32 v55, v76, v77
	v_pk_fma_f32 v[78:79], v[20:21], v[56:57], v[78:79] op_sel_hi:[1,0,1]
	v_pk_mul_f32 v[82:83], v[14:15], v[58:59] op_sel_hi:[1,0]
	v_pk_mul_f32 v[86:87], v[10:11], v[58:59] op_sel_hi:[1,0]
	v_pk_mul_f32 v[90:91], v[6:7], v[58:59] op_sel_hi:[1,0]
	global_store_dwordx4 v[72:73], v[52:55], off offset:256
	v_pk_fma_f32 v[82:83], v[24:25], v[56:57], v[82:83] op_sel_hi:[1,0,1]
	v_pk_fma_f32 v[86:87], v[12:13], v[56:57], v[86:87] op_sel_hi:[1,0,1]
	v_cvt_pk_bf16_f32 v52, v68, v69
	v_pk_mul_f32 v[68:69], v[2:3], v[58:59] op_sel_hi:[1,0]
	v_pk_fma_f32 v[90:91], v[16:17], v[56:57], v[90:91] op_sel_hi:[1,0,1]
	v_cvt_pk_bf16_f32 v53, v70, v71
	v_cvt_pk_bf16_f32 v54, v74, v75
	v_cvt_pk_bf16_f32 v55, v78, v79
	v_pk_fma_f32 v[68:69], v[4:5], v[56:57], v[68:69] op_sel_hi:[1,0,1]
	global_store_dwordx4 v[72:73], v[52:55], off offset:16
	v_cndmask_b32_e64 v38, 1, 6, vcc
	v_or_b32_e32 v38, v38, v41
	v_cvt_pk_bf16_f32 v52, v82, v83
	v_cvt_pk_bf16_f32 v53, v86, v87
	v_cvt_pk_bf16_f32 v54, v90, v91
	v_cvt_pk_bf16_f32 v55, v68, v69
	global_store_dwordx4 v[72:73], v[52:55], off offset:272
	v_lshlrev_b32_e32 v38, 9, v38
	v_lshl_add_u64 v[68:69], v[8:9], 0, v[38:39]
	v_pk_mul_f32 v[52:53], v[48:49], v[56:57] op_sel_hi:[1,0]
	v_cndmask_b32_e64 v38, 2, 5, vcc
	v_pk_fma_f32 v[56:57], v[48:49], v[58:59], v[52:53] op_sel:[0,0,1] op_sel_hi:[1,0,0] neg_lo:[1,0,0] neg_hi:[1,0,0]
	v_pk_fma_f32 v[58:59], v[48:49], v[58:59], v[52:53] op_sel:[0,0,1] op_sel_hi:[1,0,0]
	v_pk_mul_f32 v[54:55], v[50:51], v[56:57] op_sel_hi:[1,0]
	v_pk_mul_f32 v[52:53], v[50:51], v[58:59] op_sel:[0,1]
	v_pk_fma_f32 v[72:73], v[30:31], v[58:59], v[54:55] op_sel:[0,1,0]
	v_pk_mul_f32 v[54:55], v[28:29], v[58:59] op_sel:[0,1]
	v_pk_mul_f32 v[76:77], v[32:33], v[58:59] op_sel:[0,1]
	v_pk_fma_f32 v[52:53], v[30:31], v[56:57], v[52:53] op_sel_hi:[1,0,1] neg_lo:[0,0,1] neg_hi:[0,0,1]
	v_pk_fma_f32 v[54:55], v[26:27], v[56:57], v[54:55] op_sel_hi:[1,0,1] neg_lo:[0,0,1] neg_hi:[0,0,1]
	v_pk_fma_f32 v[76:77], v[22:23], v[56:57], v[76:77] op_sel_hi:[1,0,1] neg_lo:[0,0,1] neg_hi:[0,0,1]
	v_pk_mul_f32 v[80:81], v[20:21], v[58:59] op_sel:[0,1]
	v_pk_mul_f32 v[84:85], v[24:25], v[58:59] op_sel:[0,1]
	v_pk_fma_f32 v[80:81], v[18:19], v[56:57], v[80:81] op_sel_hi:[1,0,1] neg_lo:[0,0,1] neg_hi:[0,0,1]
	v_pk_mul_f32 v[88:89], v[12:13], v[58:59] op_sel:[0,1]
	v_pk_mul_f32 v[92:93], v[16:17], v[58:59] op_sel:[0,1]
	v_cvt_pk_bf16_f32 v52, v52, v53
	v_cvt_pk_bf16_f32 v53, v54, v55
	v_cvt_pk_bf16_f32 v54, v76, v77
	v_pk_mul_f32 v[76:77], v[4:5], v[58:59] op_sel:[0,1]
	v_pk_mul_f32 v[74:75], v[28:29], v[56:57] op_sel_hi:[1,0]
	v_pk_mul_f32 v[78:79], v[32:33], v[56:57] op_sel_hi:[1,0]
	v_pk_mul_f32 v[82:83], v[20:21], v[56:57] op_sel_hi:[1,0]
	v_pk_fma_f32 v[84:85], v[14:15], v[56:57], v[84:85] op_sel_hi:[1,0,1] neg_lo:[0,0,1] neg_hi:[0,0,1]
	v_pk_fma_f32 v[88:89], v[10:11], v[56:57], v[88:89] op_sel_hi:[1,0,1] neg_lo:[0,0,1] neg_hi:[0,0,1]
	v_pk_fma_f32 v[92:93], v[6:7], v[56:57], v[92:93] op_sel_hi:[1,0,1] neg_lo:[0,0,1] neg_hi:[0,0,1]
	v_cvt_pk_bf16_f32 v55, v80, v81
	v_pk_fma_f32 v[76:77], v[2:3], v[56:57], v[76:77] op_sel_hi:[1,0,1] neg_lo:[0,0,1] neg_hi:[0,0,1]
	v_mov_b32_e32 v70, v56
	v_pk_fma_f32 v[74:75], v[26:27], v[58:59], v[74:75] op_sel:[0,1,0]
	v_pk_fma_f32 v[78:79], v[22:23], v[58:59], v[78:79] op_sel:[0,1,0]
	v_pk_fma_f32 v[82:83], v[18:19], v[58:59], v[82:83] op_sel:[0,1,0]
	v_pk_mul_f32 v[86:87], v[24:25], v[56:57] op_sel_hi:[1,0]
	v_pk_mul_f32 v[90:91], v[12:13], v[56:57] op_sel_hi:[1,0]
	v_pk_mul_f32 v[94:95], v[16:17], v[56:57] op_sel_hi:[1,0]
	global_store_dwordx4 v[68:69], v[52:55], off
	v_pk_mul_f32 v[56:57], v[4:5], v[56:57] op_sel_hi:[1,0]
	v_pk_fma_f32 v[86:87], v[14:15], v[58:59], v[86:87] op_sel:[0,1,0]
	v_cvt_pk_bf16_f32 v52, v84, v85
	v_cvt_pk_bf16_f32 v53, v88, v89
	v_cvt_pk_bf16_f32 v54, v92, v93
	v_cvt_pk_bf16_f32 v55, v76, v77
	v_pk_fma_f32 v[90:91], v[10:11], v[58:59], v[90:91] op_sel:[0,1,0]
	v_pk_fma_f32 v[94:95], v[6:7], v[58:59], v[94:95] op_sel:[0,1,0]
	global_store_dwordx4 v[68:69], v[52:55], off offset:256
	v_pk_fma_f32 v[56:57], v[2:3], v[58:59], v[56:57] op_sel:[0,1,0]
	v_mov_b32_e32 v71, v59
	v_cvt_pk_bf16_f32 v52, v72, v73
	v_cvt_pk_bf16_f32 v53, v74, v75
	v_cvt_pk_bf16_f32 v54, v78, v79
	v_cvt_pk_bf16_f32 v55, v82, v83
	global_store_dwordx4 v[68:69], v[52:55], off offset:16
	v_or_b32_e32 v38, v38, v41
	v_lshlrev_b32_e32 v38, 9, v38
	v_cvt_pk_bf16_f32 v52, v86, v87
	v_cvt_pk_bf16_f32 v53, v90, v91
	v_cvt_pk_bf16_f32 v54, v94, v95
	v_cvt_pk_bf16_f32 v55, v56, v57
	global_store_dwordx4 v[68:69], v[52:55], off offset:272
	v_lshl_add_u64 v[56:57], v[8:9], 0, v[38:39]
	v_cndmask_b32_e64 v38, 3, 4, vcc
	v_pk_mul_f32 v[52:53], v[48:49], v[70:71] op_sel:[1,0] op_sel_hi:[0,1]
	v_pk_mul_f32 v[54:55], v[48:49], v[70:71]
	v_mov_b32_e32 v58, v52
	v_mov_b32_e32 v59, v54
	v_mov_b32_e32 v54, v53
	v_pk_add_f32 v[68:69], v[58:59], v[54:55] neg_lo:[0,1] neg_hi:[0,1]
	v_pk_add_f32 v[58:59], v[58:59], v[54:55]
	v_pk_mul_f32 v[54:55], v[50:51], v[68:69] op_sel_hi:[1,0]
	v_pk_mul_f32 v[52:53], v[50:51], v[58:59] op_sel:[0,1]
	v_pk_fma_f32 v[72:73], v[30:31], v[58:59], v[54:55] op_sel:[0,1,0]
	v_pk_mul_f32 v[54:55], v[28:29], v[58:59] op_sel:[0,1]
	v_pk_mul_f32 v[76:77], v[32:33], v[58:59] op_sel:[0,1]
	v_pk_fma_f32 v[52:53], v[30:31], v[68:69], v[52:53] op_sel_hi:[1,0,1] neg_lo:[0,0,1] neg_hi:[0,0,1]
	v_pk_fma_f32 v[54:55], v[26:27], v[68:69], v[54:55] op_sel_hi:[1,0,1] neg_lo:[0,0,1] neg_hi:[0,0,1]
	v_pk_fma_f32 v[76:77], v[22:23], v[68:69], v[76:77] op_sel_hi:[1,0,1] neg_lo:[0,0,1] neg_hi:[0,0,1]
	v_pk_mul_f32 v[80:81], v[20:21], v[58:59] op_sel:[0,1]
	v_pk_mul_f32 v[84:85], v[24:25], v[58:59] op_sel:[0,1]
	v_pk_fma_f32 v[80:81], v[18:19], v[68:69], v[80:81] op_sel_hi:[1,0,1] neg_lo:[0,0,1] neg_hi:[0,0,1]
	v_pk_mul_f32 v[88:89], v[12:13], v[58:59] op_sel:[0,1]
	v_pk_mul_f32 v[92:93], v[16:17], v[58:59] op_sel:[0,1]
	v_cvt_pk_bf16_f32 v52, v52, v53
	v_cvt_pk_bf16_f32 v53, v54, v55
	v_cvt_pk_bf16_f32 v54, v76, v77
	v_pk_mul_f32 v[76:77], v[4:5], v[58:59] op_sel:[0,1]
	v_pk_mul_f32 v[74:75], v[28:29], v[68:69] op_sel_hi:[1,0]
	v_pk_mul_f32 v[78:79], v[32:33], v[68:69] op_sel_hi:[1,0]
	v_pk_mul_f32 v[82:83], v[20:21], v[68:69] op_sel_hi:[1,0]
	v_pk_fma_f32 v[84:85], v[14:15], v[68:69], v[84:85] op_sel_hi:[1,0,1] neg_lo:[0,0,1] neg_hi:[0,0,1]
	v_pk_fma_f32 v[88:89], v[10:11], v[68:69], v[88:89] op_sel_hi:[1,0,1] neg_lo:[0,0,1] neg_hi:[0,0,1]
	v_pk_fma_f32 v[92:93], v[6:7], v[68:69], v[92:93] op_sel_hi:[1,0,1] neg_lo:[0,0,1] neg_hi:[0,0,1]
	v_cvt_pk_bf16_f32 v55, v80, v81
	v_pk_fma_f32 v[76:77], v[2:3], v[68:69], v[76:77] op_sel_hi:[1,0,1] neg_lo:[0,0,1] neg_hi:[0,0,1]
	v_mov_b32_e32 v70, v68
	v_pk_fma_f32 v[74:75], v[26:27], v[58:59], v[74:75] op_sel:[0,1,0]
	v_pk_fma_f32 v[78:79], v[22:23], v[58:59], v[78:79] op_sel:[0,1,0]
	v_pk_fma_f32 v[82:83], v[18:19], v[58:59], v[82:83] op_sel:[0,1,0]
	v_pk_mul_f32 v[86:87], v[24:25], v[68:69] op_sel_hi:[1,0]
	v_pk_mul_f32 v[90:91], v[12:13], v[68:69] op_sel_hi:[1,0]
	v_pk_mul_f32 v[94:95], v[16:17], v[68:69] op_sel_hi:[1,0]
	global_store_dwordx4 v[56:57], v[52:55], off
	v_pk_mul_f32 v[68:69], v[4:5], v[68:69] op_sel_hi:[1,0]
	v_mov_b32_e32 v71, v59
	v_cvt_pk_bf16_f32 v52, v84, v85
	v_cvt_pk_bf16_f32 v53, v88, v89
	v_cvt_pk_bf16_f32 v54, v92, v93
	v_cvt_pk_bf16_f32 v55, v76, v77
	v_pk_fma_f32 v[86:87], v[14:15], v[58:59], v[86:87] op_sel:[0,1,0]
	v_pk_fma_f32 v[90:91], v[10:11], v[58:59], v[90:91] op_sel:[0,1,0]
	v_pk_fma_f32 v[94:95], v[6:7], v[58:59], v[94:95] op_sel:[0,1,0]
	global_store_dwordx4 v[56:57], v[52:55], off offset:256
	v_pk_fma_f32 v[58:59], v[2:3], v[58:59], v[68:69] op_sel:[0,1,0]
	v_or_b32_e32 v38, v38, v41
	v_cvt_pk_bf16_f32 v52, v72, v73
	v_cvt_pk_bf16_f32 v53, v74, v75
	v_cvt_pk_bf16_f32 v54, v78, v79
	v_cvt_pk_bf16_f32 v55, v82, v83
	global_store_dwordx4 v[56:57], v[52:55], off offset:16
	v_lshlrev_b32_e32 v38, 9, v38
	s_mov_b32 s0, 0xffff
	v_cvt_pk_bf16_f32 v52, v86, v87
	v_cvt_pk_bf16_f32 v53, v90, v91
	v_cvt_pk_bf16_f32 v54, v94, v95
	v_cvt_pk_bf16_f32 v55, v58, v59
	global_store_dwordx4 v[56:57], v[52:55], off offset:272
	v_lshl_add_u64 v[56:57], v[8:9], 0, v[38:39]
	v_cndmask_b32_e64 v38, 4, 3, vcc
	v_pk_mul_f32 v[52:53], v[48:49], v[70:71] op_sel:[1,0] op_sel_hi:[0,1]
	v_pk_mul_f32 v[54:55], v[48:49], v[70:71]
	v_mov_b32_e32 v58, v52
	v_mov_b32_e32 v59, v54
	v_mov_b32_e32 v54, v53
	v_pk_add_f32 v[68:69], v[58:59], v[54:55] neg_lo:[0,1] neg_hi:[0,1]
	v_pk_add_f32 v[58:59], v[58:59], v[54:55]
	v_pk_mul_f32 v[54:55], v[50:51], v[68:69] op_sel_hi:[1,0]
	v_pk_mul_f32 v[52:53], v[50:51], v[58:59] op_sel:[0,1]
	v_pk_fma_f32 v[72:73], v[30:31], v[58:59], v[54:55] op_sel:[0,1,0]
	v_pk_mul_f32 v[54:55], v[28:29], v[58:59] op_sel:[0,1]
	v_pk_mul_f32 v[76:77], v[32:33], v[58:59] op_sel:[0,1]
	v_pk_fma_f32 v[52:53], v[30:31], v[68:69], v[52:53] op_sel_hi:[1,0,1] neg_lo:[0,0,1] neg_hi:[0,0,1]
	v_pk_fma_f32 v[54:55], v[26:27], v[68:69], v[54:55] op_sel_hi:[1,0,1] neg_lo:[0,0,1] neg_hi:[0,0,1]
	v_pk_fma_f32 v[76:77], v[22:23], v[68:69], v[76:77] op_sel_hi:[1,0,1] neg_lo:[0,0,1] neg_hi:[0,0,1]
	v_pk_mul_f32 v[80:81], v[20:21], v[58:59] op_sel:[0,1]
	v_pk_mul_f32 v[84:85], v[24:25], v[58:59] op_sel:[0,1]
	v_pk_fma_f32 v[80:81], v[18:19], v[68:69], v[80:81] op_sel_hi:[1,0,1] neg_lo:[0,0,1] neg_hi:[0,0,1]
	v_pk_mul_f32 v[88:89], v[12:13], v[58:59] op_sel:[0,1]
	v_pk_mul_f32 v[92:93], v[16:17], v[58:59] op_sel:[0,1]
	v_cvt_pk_bf16_f32 v52, v52, v53
	v_cvt_pk_bf16_f32 v53, v54, v55
	v_cvt_pk_bf16_f32 v54, v76, v77
	v_pk_mul_f32 v[76:77], v[4:5], v[58:59] op_sel:[0,1]
	v_pk_mul_f32 v[74:75], v[28:29], v[68:69] op_sel_hi:[1,0]
	v_pk_mul_f32 v[78:79], v[32:33], v[68:69] op_sel_hi:[1,0]
	v_pk_mul_f32 v[82:83], v[20:21], v[68:69] op_sel_hi:[1,0]
	v_pk_fma_f32 v[84:85], v[14:15], v[68:69], v[84:85] op_sel_hi:[1,0,1] neg_lo:[0,0,1] neg_hi:[0,0,1]
	v_pk_fma_f32 v[88:89], v[10:11], v[68:69], v[88:89] op_sel_hi:[1,0,1] neg_lo:[0,0,1] neg_hi:[0,0,1]
	v_pk_fma_f32 v[92:93], v[6:7], v[68:69], v[92:93] op_sel_hi:[1,0,1] neg_lo:[0,0,1] neg_hi:[0,0,1]
	v_cvt_pk_bf16_f32 v55, v80, v81
	v_pk_fma_f32 v[76:77], v[2:3], v[68:69], v[76:77] op_sel_hi:[1,0,1] neg_lo:[0,0,1] neg_hi:[0,0,1]
	v_mov_b32_e32 v70, v68
	v_pk_fma_f32 v[74:75], v[26:27], v[58:59], v[74:75] op_sel:[0,1,0]
	v_pk_fma_f32 v[78:79], v[22:23], v[58:59], v[78:79] op_sel:[0,1,0]
	v_pk_fma_f32 v[82:83], v[18:19], v[58:59], v[82:83] op_sel:[0,1,0]
	v_pk_mul_f32 v[86:87], v[24:25], v[68:69] op_sel_hi:[1,0]
	v_pk_mul_f32 v[90:91], v[12:13], v[68:69] op_sel_hi:[1,0]
	v_pk_mul_f32 v[94:95], v[16:17], v[68:69] op_sel_hi:[1,0]
	global_store_dwordx4 v[56:57], v[52:55], off
	v_pk_mul_f32 v[68:69], v[4:5], v[68:69] op_sel_hi:[1,0]
	v_mov_b32_e32 v71, v59
	v_cvt_pk_bf16_f32 v52, v84, v85
	v_cvt_pk_bf16_f32 v53, v88, v89
	v_cvt_pk_bf16_f32 v54, v92, v93
	v_cvt_pk_bf16_f32 v55, v76, v77
	v_pk_fma_f32 v[86:87], v[14:15], v[58:59], v[86:87] op_sel:[0,1,0]
	v_pk_fma_f32 v[90:91], v[10:11], v[58:59], v[90:91] op_sel:[0,1,0]
	v_pk_fma_f32 v[94:95], v[6:7], v[58:59], v[94:95] op_sel:[0,1,0]
	global_store_dwordx4 v[56:57], v[52:55], off offset:256
	v_pk_fma_f32 v[58:59], v[2:3], v[58:59], v[68:69] op_sel:[0,1,0]
	v_or_b32_e32 v38, v38, v41
	v_cvt_pk_bf16_f32 v52, v72, v73
	v_cvt_pk_bf16_f32 v53, v74, v75
	v_cvt_pk_bf16_f32 v54, v78, v79
	v_cvt_pk_bf16_f32 v55, v82, v83
	global_store_dwordx4 v[56:57], v[52:55], off offset:16
	v_lshlrev_b32_e32 v38, 9, v38
	s_nop 0
	v_cvt_pk_bf16_f32 v52, v86, v87
	v_cvt_pk_bf16_f32 v53, v90, v91
	v_cvt_pk_bf16_f32 v54, v94, v95
	v_cvt_pk_bf16_f32 v55, v58, v59
	global_store_dwordx4 v[56:57], v[52:55], off offset:272
	v_lshl_add_u64 v[56:57], v[8:9], 0, v[38:39]
	v_cndmask_b32_e64 v38, 5, 2, vcc
	v_pk_mul_f32 v[52:53], v[48:49], v[70:71] op_sel:[1,0] op_sel_hi:[0,1]
	v_pk_mul_f32 v[54:55], v[48:49], v[70:71]
	v_mov_b32_e32 v58, v52
	v_mov_b32_e32 v59, v54
	v_mov_b32_e32 v54, v53
	v_pk_add_f32 v[68:69], v[58:59], v[54:55] neg_lo:[0,1] neg_hi:[0,1]
	v_pk_add_f32 v[58:59], v[58:59], v[54:55]
	v_pk_mul_f32 v[54:55], v[50:51], v[68:69] op_sel_hi:[1,0]
	v_pk_mul_f32 v[52:53], v[50:51], v[58:59] op_sel:[0,1]
	v_pk_fma_f32 v[72:73], v[30:31], v[58:59], v[54:55] op_sel:[0,1,0]
	v_pk_mul_f32 v[54:55], v[28:29], v[58:59] op_sel:[0,1]
	v_pk_mul_f32 v[76:77], v[32:33], v[58:59] op_sel:[0,1]
	v_pk_fma_f32 v[52:53], v[30:31], v[68:69], v[52:53] op_sel_hi:[1,0,1] neg_lo:[0,0,1] neg_hi:[0,0,1]
	v_pk_fma_f32 v[54:55], v[26:27], v[68:69], v[54:55] op_sel_hi:[1,0,1] neg_lo:[0,0,1] neg_hi:[0,0,1]
	v_pk_fma_f32 v[76:77], v[22:23], v[68:69], v[76:77] op_sel_hi:[1,0,1] neg_lo:[0,0,1] neg_hi:[0,0,1]
	v_pk_mul_f32 v[80:81], v[20:21], v[58:59] op_sel:[0,1]
	v_pk_mul_f32 v[84:85], v[24:25], v[58:59] op_sel:[0,1]
	v_pk_fma_f32 v[80:81], v[18:19], v[68:69], v[80:81] op_sel_hi:[1,0,1] neg_lo:[0,0,1] neg_hi:[0,0,1]
	v_pk_mul_f32 v[88:89], v[12:13], v[58:59] op_sel:[0,1]
	v_pk_mul_f32 v[92:93], v[16:17], v[58:59] op_sel:[0,1]
	v_cvt_pk_bf16_f32 v52, v52, v53
	v_cvt_pk_bf16_f32 v53, v54, v55
	v_cvt_pk_bf16_f32 v54, v76, v77
	v_pk_mul_f32 v[76:77], v[4:5], v[58:59] op_sel:[0,1]
	v_pk_mul_f32 v[74:75], v[28:29], v[68:69] op_sel_hi:[1,0]
	v_pk_mul_f32 v[78:79], v[32:33], v[68:69] op_sel_hi:[1,0]
	v_pk_mul_f32 v[82:83], v[20:21], v[68:69] op_sel_hi:[1,0]
	v_pk_fma_f32 v[84:85], v[14:15], v[68:69], v[84:85] op_sel_hi:[1,0,1] neg_lo:[0,0,1] neg_hi:[0,0,1]
	v_pk_fma_f32 v[88:89], v[10:11], v[68:69], v[88:89] op_sel_hi:[1,0,1] neg_lo:[0,0,1] neg_hi:[0,0,1]
	v_pk_fma_f32 v[92:93], v[6:7], v[68:69], v[92:93] op_sel_hi:[1,0,1] neg_lo:[0,0,1] neg_hi:[0,0,1]
	v_cvt_pk_bf16_f32 v55, v80, v81
	v_pk_fma_f32 v[76:77], v[2:3], v[68:69], v[76:77] op_sel_hi:[1,0,1] neg_lo:[0,0,1] neg_hi:[0,0,1]
	v_mov_b32_e32 v70, v68
	v_pk_fma_f32 v[74:75], v[26:27], v[58:59], v[74:75] op_sel:[0,1,0]
	v_pk_fma_f32 v[78:79], v[22:23], v[58:59], v[78:79] op_sel:[0,1,0]
	v_pk_fma_f32 v[82:83], v[18:19], v[58:59], v[82:83] op_sel:[0,1,0]
	v_pk_mul_f32 v[86:87], v[24:25], v[68:69] op_sel_hi:[1,0]
	v_pk_mul_f32 v[90:91], v[12:13], v[68:69] op_sel_hi:[1,0]
	v_pk_mul_f32 v[94:95], v[16:17], v[68:69] op_sel_hi:[1,0]
	global_store_dwordx4 v[56:57], v[52:55], off
	v_pk_mul_f32 v[68:69], v[4:5], v[68:69] op_sel_hi:[1,0]
	v_mov_b32_e32 v71, v59
	v_cvt_pk_bf16_f32 v52, v84, v85
	v_cvt_pk_bf16_f32 v53, v88, v89
	v_cvt_pk_bf16_f32 v54, v92, v93
	v_cvt_pk_bf16_f32 v55, v76, v77
	v_pk_fma_f32 v[86:87], v[14:15], v[58:59], v[86:87] op_sel:[0,1,0]
	v_pk_fma_f32 v[90:91], v[10:11], v[58:59], v[90:91] op_sel:[0,1,0]
	v_pk_fma_f32 v[94:95], v[6:7], v[58:59], v[94:95] op_sel:[0,1,0]
	global_store_dwordx4 v[56:57], v[52:55], off offset:256
	v_pk_fma_f32 v[58:59], v[2:3], v[58:59], v[68:69] op_sel:[0,1,0]
	v_or_b32_e32 v38, v38, v41
	v_cvt_pk_bf16_f32 v52, v72, v73
	v_cvt_pk_bf16_f32 v53, v74, v75
	v_cvt_pk_bf16_f32 v54, v78, v79
	v_cvt_pk_bf16_f32 v55, v82, v83
	global_store_dwordx4 v[56:57], v[52:55], off offset:16
	v_lshlrev_b32_e32 v38, 9, v38
	s_nop 0
	v_cvt_pk_bf16_f32 v52, v86, v87
	v_cvt_pk_bf16_f32 v53, v90, v91
	v_cvt_pk_bf16_f32 v54, v94, v95
	v_cvt_pk_bf16_f32 v55, v58, v59
	global_store_dwordx4 v[56:57], v[52:55], off offset:272
	v_lshl_add_u64 v[56:57], v[8:9], 0, v[38:39]
	v_cndmask_b32_e64 v38, 6, 1, vcc
	v_pk_mul_f32 v[52:53], v[48:49], v[70:71] op_sel:[1,0] op_sel_hi:[0,1]
	v_pk_mul_f32 v[54:55], v[48:49], v[70:71]
	v_mov_b32_e32 v58, v52
	v_mov_b32_e32 v59, v54
	v_mov_b32_e32 v54, v53
	v_pk_add_f32 v[68:69], v[58:59], v[54:55] neg_lo:[0,1] neg_hi:[0,1]
	v_pk_add_f32 v[58:59], v[58:59], v[54:55]
	v_pk_mul_f32 v[54:55], v[50:51], v[68:69] op_sel_hi:[1,0]
	v_pk_mul_f32 v[52:53], v[50:51], v[58:59] op_sel:[0,1]
	v_pk_fma_f32 v[72:73], v[30:31], v[58:59], v[54:55] op_sel:[0,1,0]
	v_pk_mul_f32 v[54:55], v[28:29], v[58:59] op_sel:[0,1]
	v_pk_mul_f32 v[76:77], v[32:33], v[58:59] op_sel:[0,1]
	v_pk_fma_f32 v[52:53], v[30:31], v[68:69], v[52:53] op_sel_hi:[1,0,1] neg_lo:[0,0,1] neg_hi:[0,0,1]
	v_pk_fma_f32 v[54:55], v[26:27], v[68:69], v[54:55] op_sel_hi:[1,0,1] neg_lo:[0,0,1] neg_hi:[0,0,1]
	v_pk_fma_f32 v[76:77], v[22:23], v[68:69], v[76:77] op_sel_hi:[1,0,1] neg_lo:[0,0,1] neg_hi:[0,0,1]
	v_pk_mul_f32 v[80:81], v[20:21], v[58:59] op_sel:[0,1]
	v_pk_mul_f32 v[84:85], v[24:25], v[58:59] op_sel:[0,1]
	v_pk_fma_f32 v[80:81], v[18:19], v[68:69], v[80:81] op_sel_hi:[1,0,1] neg_lo:[0,0,1] neg_hi:[0,0,1]
	v_pk_mul_f32 v[88:89], v[12:13], v[58:59] op_sel:[0,1]
	v_pk_mul_f32 v[92:93], v[16:17], v[58:59] op_sel:[0,1]
	v_cvt_pk_bf16_f32 v52, v52, v53
	v_cvt_pk_bf16_f32 v53, v54, v55
	v_cvt_pk_bf16_f32 v54, v76, v77
	v_pk_mul_f32 v[76:77], v[4:5], v[58:59] op_sel:[0,1]
	v_pk_mul_f32 v[74:75], v[28:29], v[68:69] op_sel_hi:[1,0]
	v_pk_mul_f32 v[78:79], v[32:33], v[68:69] op_sel_hi:[1,0]
	v_pk_mul_f32 v[82:83], v[20:21], v[68:69] op_sel_hi:[1,0]
	v_pk_fma_f32 v[84:85], v[14:15], v[68:69], v[84:85] op_sel_hi:[1,0,1] neg_lo:[0,0,1] neg_hi:[0,0,1]
	v_pk_fma_f32 v[88:89], v[10:11], v[68:69], v[88:89] op_sel_hi:[1,0,1] neg_lo:[0,0,1] neg_hi:[0,0,1]
	v_pk_fma_f32 v[92:93], v[6:7], v[68:69], v[92:93] op_sel_hi:[1,0,1] neg_lo:[0,0,1] neg_hi:[0,0,1]
	v_cvt_pk_bf16_f32 v55, v80, v81
	v_pk_fma_f32 v[76:77], v[2:3], v[68:69], v[76:77] op_sel_hi:[1,0,1] neg_lo:[0,0,1] neg_hi:[0,0,1]
	v_mov_b32_e32 v70, v68
	v_pk_fma_f32 v[74:75], v[26:27], v[58:59], v[74:75] op_sel:[0,1,0]
	v_pk_fma_f32 v[78:79], v[22:23], v[58:59], v[78:79] op_sel:[0,1,0]
	v_pk_fma_f32 v[82:83], v[18:19], v[58:59], v[82:83] op_sel:[0,1,0]
	v_pk_mul_f32 v[86:87], v[24:25], v[68:69] op_sel_hi:[1,0]
	v_pk_mul_f32 v[90:91], v[12:13], v[68:69] op_sel_hi:[1,0]
	v_pk_mul_f32 v[94:95], v[16:17], v[68:69] op_sel_hi:[1,0]
	global_store_dwordx4 v[56:57], v[52:55], off
	v_pk_mul_f32 v[68:69], v[4:5], v[68:69] op_sel_hi:[1,0]
	v_mov_b32_e32 v71, v59
	v_cvt_pk_bf16_f32 v52, v84, v85
	v_cvt_pk_bf16_f32 v53, v88, v89
	v_cvt_pk_bf16_f32 v54, v92, v93
	v_cvt_pk_bf16_f32 v55, v76, v77
	v_pk_fma_f32 v[86:87], v[14:15], v[58:59], v[86:87] op_sel:[0,1,0]
	v_pk_fma_f32 v[90:91], v[10:11], v[58:59], v[90:91] op_sel:[0,1,0]
	v_pk_fma_f32 v[94:95], v[6:7], v[58:59], v[94:95] op_sel:[0,1,0]
	global_store_dwordx4 v[56:57], v[52:55], off offset:256
	v_pk_fma_f32 v[58:59], v[2:3], v[58:59], v[68:69] op_sel:[0,1,0]
	v_or_b32_e32 v38, v38, v41
	v_cvt_pk_bf16_f32 v52, v72, v73
	v_cvt_pk_bf16_f32 v53, v74, v75
	v_cvt_pk_bf16_f32 v54, v78, v79
	v_cvt_pk_bf16_f32 v55, v82, v83
	global_store_dwordx4 v[56:57], v[52:55], off offset:16
	v_lshlrev_b32_e32 v38, 9, v38
	s_nop 0
	v_cvt_pk_bf16_f32 v52, v86, v87
	v_cvt_pk_bf16_f32 v53, v90, v91
	v_cvt_pk_bf16_f32 v54, v94, v95
	v_cvt_pk_bf16_f32 v55, v58, v59
	global_store_dwordx4 v[56:57], v[52:55], off offset:272
	v_lshl_add_u64 v[56:57], v[8:9], 0, v[38:39]
	s_nop 0
	v_pk_mul_f32 v[52:53], v[48:49], v[70:71] op_sel:[1,0] op_sel_hi:[0,1]
	v_pk_mul_f32 v[54:55], v[48:49], v[70:71]
	v_mov_b32_e32 v58, v52
	v_mov_b32_e32 v59, v54
	v_mov_b32_e32 v54, v53
	v_pk_add_f32 v[68:69], v[58:59], v[54:55] neg_lo:[0,1] neg_hi:[0,1]
	v_pk_add_f32 v[58:59], v[58:59], v[54:55]
	v_pk_mul_f32 v[54:55], v[50:51], v[68:69] op_sel_hi:[1,0]
	v_pk_mul_f32 v[52:53], v[50:51], v[58:59] op_sel:[0,1]
	v_pk_fma_f32 v[72:73], v[30:31], v[58:59], v[54:55] op_sel:[0,1,0]
	v_pk_mul_f32 v[54:55], v[28:29], v[58:59] op_sel:[0,1]
	v_pk_mul_f32 v[76:77], v[32:33], v[58:59] op_sel:[0,1]
	v_pk_fma_f32 v[52:53], v[30:31], v[68:69], v[52:53] op_sel_hi:[1,0,1] neg_lo:[0,0,1] neg_hi:[0,0,1]
	v_pk_fma_f32 v[54:55], v[26:27], v[68:69], v[54:55] op_sel_hi:[1,0,1] neg_lo:[0,0,1] neg_hi:[0,0,1]
	v_pk_fma_f32 v[76:77], v[22:23], v[68:69], v[76:77] op_sel_hi:[1,0,1] neg_lo:[0,0,1] neg_hi:[0,0,1]
	v_pk_mul_f32 v[80:81], v[20:21], v[58:59] op_sel:[0,1]
	v_pk_mul_f32 v[84:85], v[24:25], v[58:59] op_sel:[0,1]
	v_pk_fma_f32 v[80:81], v[18:19], v[68:69], v[80:81] op_sel_hi:[1,0,1] neg_lo:[0,0,1] neg_hi:[0,0,1]
	v_pk_mul_f32 v[88:89], v[12:13], v[58:59] op_sel:[0,1]
	v_pk_mul_f32 v[92:93], v[16:17], v[58:59] op_sel:[0,1]
	v_cvt_pk_bf16_f32 v52, v52, v53
	v_cvt_pk_bf16_f32 v53, v54, v55
	v_cvt_pk_bf16_f32 v54, v76, v77
	v_pk_mul_f32 v[76:77], v[4:5], v[58:59] op_sel:[0,1]
	v_pk_mul_f32 v[74:75], v[28:29], v[68:69] op_sel_hi:[1,0]
	v_pk_mul_f32 v[78:79], v[32:33], v[68:69] op_sel_hi:[1,0]
	v_pk_mul_f32 v[82:83], v[20:21], v[68:69] op_sel_hi:[1,0]
	v_pk_fma_f32 v[84:85], v[14:15], v[68:69], v[84:85] op_sel_hi:[1,0,1] neg_lo:[0,0,1] neg_hi:[0,0,1]
	v_pk_fma_f32 v[88:89], v[10:11], v[68:69], v[88:89] op_sel_hi:[1,0,1] neg_lo:[0,0,1] neg_hi:[0,0,1]
	v_pk_fma_f32 v[92:93], v[6:7], v[68:69], v[92:93] op_sel_hi:[1,0,1] neg_lo:[0,0,1] neg_hi:[0,0,1]
	v_cvt_pk_bf16_f32 v55, v80, v81
	v_pk_fma_f32 v[76:77], v[2:3], v[68:69], v[76:77] op_sel_hi:[1,0,1] neg_lo:[0,0,1] neg_hi:[0,0,1]
	v_mov_b32_e32 v70, v68
	v_pk_fma_f32 v[74:75], v[26:27], v[58:59], v[74:75] op_sel:[0,1,0]
	v_pk_fma_f32 v[78:79], v[22:23], v[58:59], v[78:79] op_sel:[0,1,0]
	v_pk_fma_f32 v[82:83], v[18:19], v[58:59], v[82:83] op_sel:[0,1,0]
	v_pk_mul_f32 v[86:87], v[24:25], v[68:69] op_sel_hi:[1,0]
	v_pk_mul_f32 v[90:91], v[12:13], v[68:69] op_sel_hi:[1,0]
	v_pk_mul_f32 v[94:95], v[16:17], v[68:69] op_sel_hi:[1,0]
	global_store_dwordx4 v[56:57], v[52:55], off
	v_pk_mul_f32 v[68:69], v[4:5], v[68:69] op_sel_hi:[1,0]
	v_mov_b32_e32 v71, v59
	v_cvt_pk_bf16_f32 v52, v84, v85
	v_cvt_pk_bf16_f32 v53, v88, v89
	v_cvt_pk_bf16_f32 v54, v92, v93
	v_cvt_pk_bf16_f32 v55, v76, v77
	v_pk_fma_f32 v[86:87], v[14:15], v[58:59], v[86:87] op_sel:[0,1,0]
	v_pk_fma_f32 v[90:91], v[10:11], v[58:59], v[90:91] op_sel:[0,1,0]
	v_pk_fma_f32 v[94:95], v[6:7], v[58:59], v[94:95] op_sel:[0,1,0]
	global_store_dwordx4 v[56:57], v[52:55], off offset:256
	v_pk_fma_f32 v[58:59], v[2:3], v[58:59], v[68:69] op_sel:[0,1,0]
	s_nop 0
	v_cvt_pk_bf16_f32 v52, v72, v73
	v_cvt_pk_bf16_f32 v53, v74, v75
	v_cvt_pk_bf16_f32 v54, v78, v79
	v_cvt_pk_bf16_f32 v55, v82, v83
	global_store_dwordx4 v[56:57], v[52:55], off offset:16
	s_nop 1
	v_cvt_pk_bf16_f32 v52, v86, v87
	v_cvt_pk_bf16_f32 v53, v90, v91
	v_cvt_pk_bf16_f32 v54, v94, v95
	v_cvt_pk_bf16_f32 v55, v58, v59
	global_store_dwordx4 v[56:57], v[52:55], off offset:272
	s_nop 1
	v_pk_mul_f32 v[52:53], v[48:49], v[70:71] op_sel:[1,0] op_sel_hi:[0,1]
	v_pk_mul_f32 v[48:49], v[48:49], v[70:71]
	v_sub_f32_e32 v52, v52, v53
	v_add_f32_e32 v48, v48, v49
	v_pk_mul_f32 v[54:55], v[50:51], v[48:49] op_sel_hi:[1,0]
	v_pk_mul_f32 v[50:51], v[50:51], v[52:53] op_sel_hi:[1,0]
	v_pk_fma_f32 v[54:55], v[30:31], v[52:53], v[54:55] op_sel_hi:[1,0,1] neg_lo:[0,0,1] neg_hi:[0,0,1]
	v_pk_fma_f32 v[30:31], v[30:31], v[48:49], v[50:51] op_sel_hi:[1,0,1]
	v_pk_mul_f32 v[50:51], v[28:29], v[48:49] op_sel_hi:[1,0]
	v_pk_mul_f32 v[28:29], v[28:29], v[52:53] op_sel_hi:[1,0]
	v_pk_fma_f32 v[50:51], v[26:27], v[52:53], v[50:51] op_sel_hi:[1,0,1] neg_lo:[0,0,1] neg_hi:[0,0,1]
	v_pk_fma_f32 v[26:27], v[26:27], v[48:49], v[28:29] op_sel_hi:[1,0,1]
	v_pk_mul_f32 v[28:29], v[32:33], v[48:49] op_sel_hi:[1,0]
	v_pk_mul_f32 v[32:33], v[32:33], v[52:53] op_sel_hi:[1,0]
	v_pk_fma_f32 v[28:29], v[22:23], v[52:53], v[28:29] op_sel_hi:[1,0,1] neg_lo:[0,0,1] neg_hi:[0,0,1]
	v_pk_fma_f32 v[22:23], v[22:23], v[48:49], v[32:33] op_sel_hi:[1,0,1]
	v_pk_mul_f32 v[32:33], v[20:21], v[48:49] op_sel_hi:[1,0]
	v_pk_mul_f32 v[20:21], v[20:21], v[52:53] op_sel_hi:[1,0]
	v_pk_fma_f32 v[32:33], v[18:19], v[52:53], v[32:33] op_sel_hi:[1,0,1] neg_lo:[0,0,1] neg_hi:[0,0,1]
	v_pk_fma_f32 v[18:19], v[18:19], v[48:49], v[20:21] op_sel_hi:[1,0,1]
	v_pk_mul_f32 v[20:21], v[24:25], v[48:49] op_sel_hi:[1,0]
	v_pk_mul_f32 v[24:25], v[24:25], v[52:53] op_sel_hi:[1,0]
	v_pk_fma_f32 v[20:21], v[14:15], v[52:53], v[20:21] op_sel_hi:[1,0,1] neg_lo:[0,0,1] neg_hi:[0,0,1]
	v_pk_fma_f32 v[14:15], v[14:15], v[48:49], v[24:25] op_sel_hi:[1,0,1]
	v_pk_mul_f32 v[24:25], v[12:13], v[48:49] op_sel_hi:[1,0]
	v_pk_mul_f32 v[12:13], v[12:13], v[52:53] op_sel_hi:[1,0]
	v_pk_fma_f32 v[24:25], v[10:11], v[52:53], v[24:25] op_sel_hi:[1,0,1] neg_lo:[0,0,1] neg_hi:[0,0,1]
	v_pk_fma_f32 v[56:57], v[10:11], v[48:49], v[12:13] op_sel_hi:[1,0,1]
	v_pk_mul_f32 v[10:11], v[16:17], v[48:49] op_sel_hi:[1,0]
	v_cvt_pk_bf16_f32 v12, v28, v29
	v_pk_fma_f32 v[58:59], v[6:7], v[52:53], v[10:11] op_sel_hi:[1,0,1] neg_lo:[0,0,1] neg_hi:[0,0,1]
	v_pk_mul_f32 v[10:11], v[16:17], v[52:53] op_sel_hi:[1,0]
	v_cvt_pk_bf16_f32 v13, v32, v33
	v_pk_fma_f32 v[16:17], v[6:7], v[48:49], v[10:11] op_sel_hi:[1,0,1]
	v_cndmask_b32_e32 v6, v43, v41, vcc
	v_lshlrev_b32_e32 v38, 9, v6
	v_cvt_pk_bf16_f32 v10, v54, v55
	v_cvt_pk_bf16_f32 v11, v50, v51
	v_lshl_add_u64 v[28:29], v[8:9], 0, v[38:39]
	global_store_dwordx4 v[28:29], v[10:13], off
	v_cvt_pk_bf16_f32 v6, v20, v21
	v_cvt_pk_bf16_f32 v7, v24, v25
	v_pk_mul_f32 v[10:11], v[4:5], v[48:49] op_sel_hi:[1,0]
	v_cvt_pk_bf16_f32 v8, v58, v59
	v_pk_fma_f32 v[10:11], v[2:3], v[52:53], v[10:11] op_sel_hi:[1,0,1] neg_lo:[0,0,1] neg_hi:[0,0,1]
	v_pk_mul_f32 v[4:5], v[4:5], v[52:53] op_sel_hi:[1,0]
	v_cvt_pk_bf16_f32 v9, v10, v11
	global_store_dwordx4 v[28:29], v[6:9], off offset:256
	v_pk_fma_f32 v[2:3], v[2:3], v[48:49], v[4:5] op_sel_hi:[1,0,1]
	v_cmp_lt_i32_e32 vcc, s0, v66
	v_cvt_pk_bf16_f32 v6, v30, v31
	v_cvt_pk_bf16_f32 v7, v26, v27
	v_cvt_pk_bf16_f32 v8, v22, v23
	v_cvt_pk_bf16_f32 v9, v18, v19
	global_store_dwordx4 v[28:29], v[6:9], off offset:16
	s_or_b64 s[28:29], vcc, s[28:29]
	s_nop 0
	v_cvt_pk_bf16_f32 v6, v14, v15
	v_cvt_pk_bf16_f32 v7, v56, v57
	v_cvt_pk_bf16_f32 v8, v16, v17
	v_cvt_pk_bf16_f32 v9, v2, v3
	global_store_dwordx4 v[28:29], v[6:9], off offset:272
	s_andn2_b64 exec, exec, s[28:29]
	s_cbranch_execz .LBB0_40

.LBB0_416:
	v_readlane_b32 s72, v255, 40
	v_readlane_b32 s56, v250, 24
	v_readlane_b32 s73, v255, 41
	s_cmpk_gt_i32 s0, 0x4ff
	v_readlane_b32 s57, v250, 25
	v_readlane_b32 s58, v250, 26
	v_readlane_b32 s59, v250, 27
	s_mov_b32 s73, 0x800000
	v_readlane_b32 s60, v250, 28
	v_readlane_b32 s61, v250, 29
	v_readlane_b32 s62, v250, 30
	v_readlane_b32 s63, v250, 31
	v_readlane_b32 s64, v250, 32
	v_readlane_b32 s65, v250, 33
	v_readlane_b32 s66, v250, 34
	v_readlane_b32 s67, v250, 35
	v_readlane_b32 s68, v250, 36
	v_readlane_b32 s69, v250, 37
	v_readlane_b32 s70, v250, 38
	v_readlane_b32 s71, v250, 39
	s_cbranch_scc1 .LBB0_421
	v_lshlrev_b32_e32 v0, 6, v96
	v_and_b32_e32 v58, 0xc0, v0
	v_lshrrev_b32_e32 v0, 5, v96
	v_and_b32_e32 v33, 15, v97
	v_readlane_b32 s1, v255, 48
	v_mul_u32_u24_e32 v0, 0x5c00, v0
	v_and_b32_e32 v192, 48, v97
	s_lshl_b32 s1, s1, 6
	v_lshlrev_b32_e32 v32, 4, v96
	v_and_or_b32 v34, v97, 16, v0
	v_mov_b32_e32 v35, v193

.LBB0_419:
	v_lshl_add_u64 v[56:57], s[16:17], 0, v[38:39]
	v_add_co_u32_e32 v98, vcc, s97, v56
	s_nop 1
	v_addc_co_u32_e32 v99, vcc, 0, v57, vcc
	global_load_dwordx4 v[40:43], v[98:99], off offset:1024
	s_mov_b32 s24, 0xd14c000
	v_add_co_u32_e32 v98, vcc, s24, v56
	s_nop 1
	v_addc_co_u32_e32 v99, vcc, 0, v57, vcc
	global_load_dwordx4 v[44:47], v[98:99], off offset:3072
	s_mov_b32 s24, 0xd158000
	v_add_co_u32_e32 v98, vcc, s24, v56
	s_nop 1
	v_addc_co_u32_e32 v99, vcc, 0, v57, vcc
	global_load_dwordx4 v[48:51], v[98:99], off offset:1024
	s_mov_b32 s24, 0xd163000
	v_add_co_u32_e32 v98, vcc, s24, v56
	s_nop 1
	v_addc_co_u32_e32 v99, vcc, 0, v57, vcc
	global_load_dwordx4 v[52:55], v[98:99], off offset:3072
	v_lshl_add_u64 v[56:57], s[16:17], 0, v[36:37]
	s_mov_b32 s24, 0x33fb8000
	v_add_co_u32_e32 v98, vcc, s24, v56
	s_nop 1
	v_addc_co_u32_e32 v99, vcc, 0, v57, vcc
	global_load_dwordx4 v[60:63], v[98:99], off
	global_load_dwordx4 v[64:67], v[98:99], off offset:1024
	global_load_dwordx4 v[68:71], v[98:99], off offset:2048
	global_load_dwordx4 v[72:75], v[98:99], off offset:3072
	s_mov_b32 s24, 0x33fc0000
	v_add_co_u32_e32 v98, vcc, s24, v56
	s_nop 1
	v_addc_co_u32_e32 v99, vcc, 0, v57, vcc
	global_load_dwordx4 v[76:79], v[98:99], off
	global_load_dwordx4 v[80:83], v[98:99], off offset:1024
	global_load_dwordx4 v[84:87], v[98:99], off offset:2048
	global_load_dwordx4 v[88:91], v[98:99], off offset:3072
	s_mov_b32 s24, 0x33fc8000
	v_add_co_u32_e32 v98, vcc, s24, v56
	s_nop 1
	v_addc_co_u32_e32 v99, vcc, 0, v57, vcc
	global_load_dwordx4 v[92:95], v[98:99], off
	global_load_dwordx4 v[100:103], v[98:99], off offset:1024
	global_load_dwordx4 v[104:107], v[98:99], off offset:2048
	global_load_dwordx4 v[108:111], v[98:99], off offset:3072
	s_mov_b32 s24, 0x33fd0000
	v_add_co_u32_e32 v98, vcc, s24, v56
	s_nop 1
	v_addc_co_u32_e32 v99, vcc, 0, v57, vcc
	global_load_dwordx4 v[112:115], v[98:99], off
	global_load_dwordx4 v[116:119], v[98:99], off offset:1024
	global_load_dwordx4 v[120:123], v[98:99], off offset:2048
	global_load_dwordx4 v[124:127], v[98:99], off offset:3072
	s_mov_b32 s24, 0x33fd8000
	v_add_co_u32_e32 v98, vcc, s24, v56
	s_nop 1
	v_addc_co_u32_e32 v99, vcc, 0, v57, vcc
	global_load_dwordx4 v[128:131], v[98:99], off
	global_load_dwordx4 v[132:135], v[98:99], off offset:1024
	global_load_dwordx4 v[136:139], v[98:99], off offset:2048
	global_load_dwordx4 v[140:143], v[98:99], off offset:3072
	s_mov_b32 s24, 0x33fe0000
	v_add_co_u32_e32 v98, vcc, s24, v56
	s_nop 1
	v_addc_co_u32_e32 v99, vcc, 0, v57, vcc
	global_load_dwordx4 v[144:147], v[98:99], off
	global_load_dwordx4 v[148:151], v[98:99], off offset:1024
	global_load_dwordx4 v[152:155], v[98:99], off offset:2048
	global_load_dwordx4 v[156:159], v[98:99], off offset:3072
	s_mov_b32 s24, 0x33fe8000
	v_add_co_u32_e32 v98, vcc, s24, v56
	s_nop 1
	v_addc_co_u32_e32 v99, vcc, 0, v57, vcc
	global_load_dwordx4 v[160:163], v[98:99], off
	global_load_dwordx4 v[164:167], v[98:99], off offset:1024
	global_load_dwordx4 v[168:171], v[98:99], off offset:2048
	global_load_dwordx4 v[172:175], v[98:99], off offset:3072
	s_mov_b32 s24, 0x33ff0000
	v_add_co_u32_e32 v98, vcc, s24, v56
	s_nop 1
	v_addc_co_u32_e32 v99, vcc, 0, v57, vcc
	global_load_dwordx4 v[176:179], v[98:99], off
	global_load_dwordx4 v[180:183], v[98:99], off offset:1024
	global_load_dwordx4 v[184:187], v[98:99], off offset:2048
	global_load_dwordx4 v[188:191], v[98:99], off offset:3072
	s_mov_b64 s[24:25], 0x1000
	v_lshl_add_u64 v[36:37], v[36:37], 0, s[24:25]
	s_mov_b64 s[24:25], 0x2e000
	v_lshl_add_u64 v[38:39], v[38:39], 0, s[24:25]
	s_waitcnt vmcnt(31)
	v_mfma_f32_16x16x32_bf16 v[24:27], v[60:63], v[40:43], v[24:27]
	s_waitcnt vmcnt(30)
	v_mfma_f32_16x16x32_bf16 v[24:27], v[64:67], v[44:47], v[24:27]
	s_waitcnt vmcnt(29)
	v_mfma_f32_16x16x32_bf16 v[24:27], v[68:71], v[48:51], v[24:27]
	s_waitcnt vmcnt(28)
	v_mfma_f32_16x16x32_bf16 v[24:27], v[72:75], v[52:55], v[24:27]
	s_waitcnt vmcnt(27)
	v_mfma_f32_16x16x32_bf16 v[28:31], v[76:79], v[40:43], v[28:31]
	s_waitcnt vmcnt(26)
	v_mfma_f32_16x16x32_bf16 v[28:31], v[80:83], v[44:47], v[28:31]
	s_waitcnt vmcnt(25)
	v_mfma_f32_16x16x32_bf16 v[28:31], v[84:87], v[48:51], v[28:31]
	s_waitcnt vmcnt(24)
	v_mfma_f32_16x16x32_bf16 v[28:31], v[88:91], v[52:55], v[28:31]
	s_waitcnt vmcnt(23)
	v_mfma_f32_16x16x32_bf16 v[20:23], v[92:95], v[40:43], v[20:23]
	s_waitcnt vmcnt(22)
	v_mfma_f32_16x16x32_bf16 v[20:23], v[100:103], v[44:47], v[20:23]
	s_waitcnt vmcnt(21)
	v_mfma_f32_16x16x32_bf16 v[20:23], v[104:107], v[48:51], v[20:23]
	s_waitcnt vmcnt(20)
	v_mfma_f32_16x16x32_bf16 v[20:23], v[108:111], v[52:55], v[20:23]
	s_waitcnt vmcnt(19)
	v_mfma_f32_16x16x32_bf16 v[16:19], v[112:115], v[40:43], v[16:19]
	s_waitcnt vmcnt(18)
	v_mfma_f32_16x16x32_bf16 v[16:19], v[116:119], v[44:47], v[16:19]
	s_waitcnt vmcnt(17)
	v_mfma_f32_16x16x32_bf16 v[16:19], v[120:123], v[48:51], v[16:19]
	s_waitcnt vmcnt(16)
	v_mfma_f32_16x16x32_bf16 v[16:19], v[124:127], v[52:55], v[16:19]
	s_waitcnt vmcnt(15)
	v_mfma_f32_16x16x32_bf16 v[12:15], v[128:131], v[40:43], v[12:15]
	s_waitcnt vmcnt(14)
	v_mfma_f32_16x16x32_bf16 v[12:15], v[132:135], v[44:47], v[12:15]
	s_waitcnt vmcnt(13)
	v_mfma_f32_16x16x32_bf16 v[12:15], v[136:139], v[48:51], v[12:15]
	s_waitcnt vmcnt(12)
	v_mfma_f32_16x16x32_bf16 v[12:15], v[140:143], v[52:55], v[12:15]
	s_waitcnt vmcnt(11)
	v_mfma_f32_16x16x32_bf16 v[8:11], v[144:147], v[40:43], v[8:11]
	s_waitcnt vmcnt(10)
	v_mfma_f32_16x16x32_bf16 v[8:11], v[148:151], v[44:47], v[8:11]
	s_waitcnt vmcnt(9)
	v_mfma_f32_16x16x32_bf16 v[8:11], v[152:155], v[48:51], v[8:11]
	s_waitcnt vmcnt(8)
	v_mfma_f32_16x16x32_bf16 v[8:11], v[156:159], v[52:55], v[8:11]
	s_waitcnt vmcnt(7)
	v_mfma_f32_16x16x32_bf16 v[4:7], v[160:163], v[40:43], v[4:7]
	s_waitcnt vmcnt(6)
	v_mfma_f32_16x16x32_bf16 v[4:7], v[164:167], v[44:47], v[4:7]
	s_waitcnt vmcnt(5)
	v_mfma_f32_16x16x32_bf16 v[4:7], v[168:171], v[48:51], v[4:7]
	s_waitcnt vmcnt(4)
	v_mfma_f32_16x16x32_bf16 v[4:7], v[172:175], v[52:55], v[4:7]
	s_waitcnt vmcnt(3)
	v_mfma_f32_16x16x32_bf16 v[0:3], v[176:179], v[40:43], v[0:3]
	s_waitcnt vmcnt(2)
	v_mfma_f32_16x16x32_bf16 v[0:3], v[180:183], v[44:47], v[0:3]
	s_waitcnt vmcnt(1)
	v_mfma_f32_16x16x32_bf16 v[0:3], v[184:187], v[48:51], v[0:3]
	s_waitcnt vmcnt(0)
	v_mfma_f32_16x16x32_bf16 v[0:3], v[188:191], v[52:55], v[0:3]
	s_add_i32 s28, s28, -4
	s_cmp_eq_u32 s28, 0
	s_cbranch_scc0 .LBB0_419
	v_lshl_or_b32 v36, v59, 5, s21
	s_ashr_i32 s20, s20, 5
	v_ashrrev_i32_e32 v37, 31, v36
	s_ashr_i32 s21, s20, 31
	v_lshlrev_b64 v[36:37], 10, v[36:37]
	s_lshl_b64 s[20:21], s[20:21], 9
	v_lshl_add_u64 v[36:37], s[22:23], 0, v[36:37]
	v_lshl_add_u64 v[36:37], v[36:37], 0, s[20:21]
	s_add_i32 s0, s0, s8
	v_lshl_add_u64 v[36:37], v[36:37], 0, v[192:193]
	s_cmpk_gt_i32 s0, 0x4ff
	global_store_dwordx4 v[36:37], v[24:27], off
	global_store_dwordx4 v[36:37], v[28:31], off offset:64
	global_store_dwordx4 v[36:37], v[20:23], off offset:128
	global_store_dwordx4 v[36:37], v[16:19], off offset:192
	global_store_dwordx4 v[36:37], v[12:15], off offset:256
	global_store_dwordx4 v[36:37], v[8:11], off offset:320
	global_store_dwordx4 v[36:37], v[4:7], off offset:384
	global_store_dwordx4 v[36:37], v[0:3], off offset:448
	s_cbranch_scc0 .LBB0_418
